# SSD xw stage: w[j] computed once per lane for both rows, LDS reads issued up front
# speedup vs baseline: 1.0126x; 1.0029x over previous
; __device__ __forceinline__ unsigned cvt_pk(float lo, float hi) { f32x2 v = {lo, hi}; bf16x2_t b = __builtin_convertvector(v, bf16x2_t); return __builtin_bit_cast(unsigned, b); }
; __device__ __forceinline__ u32x2 pack4(f32x4 v) { u32x2 r; r.x = cvt_pk(v[0], v[1]); r.y = cvt_pk(v[2], v[3]); return r; }
; __device__ __forceinline__ float bflo(unsigned w) { return __uint_as_float(w << 16); }
; __device__ __forceinline__ float bfhi(unsigned w) { return __uint_as_float(w & 0xffff0000u); }
; __device__ __forceinline__ void ssd_prompt_item(const Params& p, int item, const int wv) {
;     ...
;     const float alast = acum_l[127];
; #pragma unroll
;     for (int r2 = 0; r2 < 2; ++r2) {
;       int pp = (tid >> 4) + 32 * r2, jc = tid & 15;
;       u32x4 xv = *(const u32x4*)(xT_l + pp * 136 + jc * 8);
;       float wj[8];
; #pragma unroll
;       for (int e = 0; e < 8; ++e) wj[e] = dt_l[jc * 8 + e] * __expf(alast - acum_l[jc * 8 + e]);
;       u32x4 ov;
;       ov.x = cvt_pk(bflo(xv.x) * wj[0], bfhi(xv.x) * wj[1]); ov.y = cvt_pk(bflo(xv.y) * wj[2], bfhi(xv.y) * wj[3]);
;       ov.z = cvt_pk(bflo(xv.z) * wj[4], bfhi(xv.z) * wj[5]); ov.w = cvt_pk(bflo(xv.w) * wj[6], bfhi(xv.w) * wj[7]);
;       *(u32x4*)(xw_l + pp * 136 + jc * 8) = ov;
;     }
;     __syncthreads();
;     {
;       const int i = wid * 16 + fr;
;       const float ai = acum_l[i];
; #pragma unroll
;       for (int jb = 0; jb < 8; ++jb) {
;         f32x4 gv = {0.f, 0.f, 0.f, 0.f};
;         if (jb <= wid) {
;           f32x4 aj = *(const f32x4*)(acum_l + jb * 16 + fq * 4);
;           f32x4 dj = *(const f32x4*)(dt_l + jb * 16 + fq * 4);
; #pragma unroll
;           for (int e = 0; e < 4; ++e) { int j = jb * 16 + fq * 4 + e; gv[e] = (j <= i) ? cb[jb][e] * __expf(ai - aj[e]) * dj[e] : 0.f; }
;         }
;         *(u32x2*)(G_l + i * 136 + jb * 16 + fq * 4) = pack4(gv);
;       }
;     }
.LBB0_593:
	v_mov_b32_e32 v128, s39
	ds_read_b32 v227, v128
	ds_read_b128 v[228:231], v213
	ds_read_b128 v[232:235], v215
	ds_read_b128 v[32:35], v211
	ds_read_b128 v[36:39], v214
	ds_read_b128 v[128:131], v212
	ds_read_b128 v[150:153], v212 offset:8704
	s_mov_b32 s41, 0x5040100
	s_and_b64 vcc, exec, s[96:97]
	s_waitcnt lgkmcnt(5)
	v_sub_f32_e32 v154, v227, v228
	v_sub_f32_e32 v155, v227, v229
	v_sub_f32_e32 v156, v227, v230
	v_sub_f32_e32 v157, v227, v231
	v_mul_f32_e32 v154, 0x3fb8aa3b, v154
	v_mul_f32_e32 v155, 0x3fb8aa3b, v155
	v_mul_f32_e32 v156, 0x3fb8aa3b, v156
	v_mul_f32_e32 v157, 0x3fb8aa3b, v157
	v_exp_f32_e32 v154, v154
	v_exp_f32_e32 v155, v155
	v_exp_f32_e32 v156, v156
	v_exp_f32_e32 v157, v157
	s_waitcnt lgkmcnt(4)
	v_sub_f32_e32 v162, v227, v232
	v_sub_f32_e32 v163, v227, v233
	v_sub_f32_e32 v164, v227, v234
	v_sub_f32_e32 v165, v227, v235
	v_mul_f32_e32 v162, 0x3fb8aa3b, v162
	v_mul_f32_e32 v163, 0x3fb8aa3b, v163
	v_mul_f32_e32 v164, 0x3fb8aa3b, v164
	v_mul_f32_e32 v165, 0x3fb8aa3b, v165
	v_exp_f32_e32 v162, v162
	v_exp_f32_e32 v163, v163
	v_exp_f32_e32 v164, v164
	v_exp_f32_e32 v165, v165
	s_waitcnt lgkmcnt(3)
	v_pk_mul_f32 v[154:155], v[32:33], v[154:155]
	v_pk_mul_f32 v[156:157], v[34:35], v[156:157]
	s_waitcnt lgkmcnt(2)
	v_pk_mul_f32 v[162:163], v[36:37], v[162:163]
	v_pk_mul_f32 v[164:165], v[38:39], v[164:165]
	s_waitcnt lgkmcnt(1)
	v_lshlrev_b32_e32 v170, 16, v128
	v_and_b32_e32 v171, 0xffff0000, v128
	v_lshlrev_b32_e32 v172, 16, v129
	v_and_b32_e32 v173, 0xffff0000, v129
	v_lshlrev_b32_e32 v236, 16, v130
	v_and_b32_e32 v237, 0xffff0000, v130
	v_lshlrev_b32_e32 v238, 16, v131
	v_and_b32_e32 v239, 0xffff0000, v131
	v_pk_mul_f32 v[170:171], v[154:155], v[170:171]
	v_pk_mul_f32 v[172:173], v[156:157], v[172:173]
	v_pk_mul_f32 v[236:237], v[162:163], v[236:237]
	v_pk_mul_f32 v[238:239], v[164:165], v[238:239]
	v_cvt_pk_bf16_f32 v128, v170, v171
	v_cvt_pk_bf16_f32 v129, v172, v173
	v_cvt_pk_bf16_f32 v130, v236, v237
	v_cvt_pk_bf16_f32 v131, v238, v239
	ds_write_b128 v216, v[128:131]
	s_waitcnt lgkmcnt(1)
	v_lshlrev_b32_e32 v170, 16, v150
	v_and_b32_e32 v171, 0xffff0000, v150
	v_lshlrev_b32_e32 v172, 16, v151
	v_and_b32_e32 v173, 0xffff0000, v151
	v_lshlrev_b32_e32 v236, 16, v152
	v_and_b32_e32 v237, 0xffff0000, v152
	v_lshlrev_b32_e32 v238, 16, v153
	v_and_b32_e32 v239, 0xffff0000, v153
	v_pk_mul_f32 v[170:171], v[154:155], v[170:171]
	v_pk_mul_f32 v[172:173], v[156:157], v[172:173]
	v_pk_mul_f32 v[236:237], v[162:163], v[236:237]
	v_pk_mul_f32 v[238:239], v[164:165], v[238:239]
	v_cvt_pk_bf16_f32 v150, v170, v171
	v_cvt_pk_bf16_f32 v151, v172, v173
	v_cvt_pk_bf16_f32 v152, v236, v237
	v_cvt_pk_bf16_f32 v153, v238, v239
	ds_write_b128 v216, v[150:153] offset:8704
	s_waitcnt lgkmcnt(0)
	s_barrier
	ds_read_b32 v128, v197
	ds_read_b128 v[228:231], v198
	ds_read_b128 v[232:235], v199
	s_waitcnt lgkmcnt(1)
	v_sub_f32_e32 v129, v128, v228
	v_mul_f32_e32 v129, 0x3fb8aa3b, v129
	v_exp_f32_e32 v129, v129
	s_nop 0
	v_mul_f32_e32 v124, v124, v129
	s_waitcnt lgkmcnt(0)
	v_mul_f32_e32 v124, v232, v124
	v_cndmask_b32_e64 v130, v124, 0, s[18:19]
	v_sub_f32_e32 v124, v128, v229
	v_mul_f32_e32 v124, 0x3fb8aa3b, v124
	v_exp_f32_e32 v124, v124
	v_mov_b32_e32 v129, 0
	v_mul_f32_e32 v124, v125, v124
	v_mul_f32_e32 v124, v233, v124
	v_cndmask_b32_e64 v131, 0, v124, s[20:21]
	v_sub_f32_e32 v124, v128, v230
	v_sub_f32_e32 v125, v128, v231
	v_mul_f32_e32 v124, 0x3fb8aa3b, v124
	v_mul_f32_e32 v125, 0x3fb8aa3b, v125
	v_exp_f32_e32 v124, v124
	v_exp_f32_e32 v125, v125
	s_nop 0
	v_pk_mul_f32 v[124:125], v[126:127], v[124:125]
	s_nop 0
	v_pk_mul_f32 v[124:125], v[234:235], v[124:125]
	v_cvt_pk_bf16_f32 v126, v130, v131
	v_cvt_pk_bf16_f32 v124, v124, v125
	v_cndmask_b32_e64 v125, v124, 0, s[24:25]
	v_lshrrev_b32_e32 v124, 16, v124
	v_cndmask_b32_e64 v124, v124, 0, s[22:23]
	v_perm_b32 v127, v124, v125, s41
	v_add_u32_e32 v124, v195, v194
	ds_write_b64 v124, v[126:127] offset:34816
	v_mov_b32_e32 v125, 0
	v_mov_b32_e32 v126, 0
	v_mov_b32_e32 v127, 0
	v_mov_b32_e32 v130, 0
	s_cbranch_vccnz .LBB0_595
	ds_read_b128 v[228:231], v198 offset:64
	ds_read_b128 v[232:235], v199 offset:64
	v_readlane_b32 s96, v250, 45
	v_readlane_b32 s97, v250, 46
	s_waitcnt lgkmcnt(1)
	v_sub_f32_e32 v125, v128, v228
	v_sub_f32_e32 v126, v128, v229
	v_mul_f32_e32 v125, 0x3fb8aa3b, v125
	v_mul_f32_e32 v127, 0x3fb8aa3b, v126
	v_exp_f32_e32 v126, v125
	v_exp_f32_e32 v127, v127
	v_sub_f32_e32 v125, v128, v230
	v_mul_f32_e32 v125, 0x3fb8aa3b, v125
	v_exp_f32_e32 v130, v125
	v_sub_f32_e32 v125, v128, v231
	v_mul_f32_e32 v125, 0x3fb8aa3b, v125
	v_exp_f32_e32 v131, v125
	v_pk_mul_f32 v[120:121], v[120:121], v[126:127]
	v_pk_mul_f32 v[122:123], v[122:123], v[130:131]
	s_waitcnt lgkmcnt(0)
	v_pk_mul_f32 v[120:121], v[232:233], v[120:121]
	v_pk_mul_f32 v[122:123], v[234:235], v[122:123]
	v_cndmask_b32_e64 v125, v120, 0, s[96:97]
	v_readlane_b32 s96, v250, 43
	v_readlane_b32 s97, v250, 44
	s_nop 1
	v_cndmask_b32_e64 v126, v121, 0, s[96:97]
	v_readlane_b32 s96, v250, 41
	v_readlane_b32 s97, v250, 42
	s_nop 1
	v_cndmask_b32_e64 v127, v122, 0, s[96:97]
	v_readlane_b32 s96, v250, 39
	v_readlane_b32 s97, v250, 40
	s_nop 1
	v_cndmask_b32_e64 v130, v123, 0, s[96:97]
